# six of the eight phase seams use a shorter barrier protocol (per-XCD arrival, one write-back, single top counter polled by all workgroups)
# speedup vs baseline: 1.0177x; 1.0062x over previous
; __device__ __forceinline__ void xcd_barrier_complete(unsigned* bar, unsigned x, unsigned& nloc, unsigned& nx) {
;     ...
;     nloc = mine > 0u ? mine : 1u; nx = cnt > 0u ? cnt : 1u;
; }
; __device__ __forceinline__ void xcd_barrier(const XcdBarrier& b) {
;     asm volatile("s_waitcnt vmcnt(0)" ::: "memory");
;     __syncthreads();
;     if (threadIdx.x == 0) {
;         unsigned* bar = b.bar;
;         __builtin_amdgcn_s_waitcnt(0);
;         unsigned nloc = b.st[0], nx = b.st[1];
;         if (nloc == 0u) { xcd_barrier_complete(bar, b.x, nloc, nx); b.st[0] = nloc; b.st[1] = nx; }
.Lg0_pub:
	v_mov_b32_e32 v0, 0x25100
	v_mov_b32_e32 v2, s14
	v_mov_b32_e32 v3, s17
	ds_write_b64 v0, v[2:3]
	v_mov_b32_e32 v1, 1
	ds_write_b32 v0, v1 offset:8

; __device__ __forceinline__ unsigned xb_ld(unsigned* p)              { return __hip_atomic_load(p, __ATOMIC_RELAXED, __HIP_MEMORY_SCOPE_AGENT); }
; __device__ __forceinline__ unsigned xb_add(unsigned* p, unsigned v) { return __hip_atomic_fetch_add(p, v, __ATOMIC_RELAXED, __HIP_MEMORY_SCOPE_AGENT); }
; #define XB_SPIN(cond, bar) do { unsigned _sp = 0; while (cond) { __builtin_amdgcn_s_sleep(1); \
;     if ((++_sp & 255u) == 0u) { if (xb_ld(&(bar)[XB_TMO])) break; if (_sp > XB_SPIN_CAP) { atomicAdd(&(bar)[XB_TMO], 1u); break; } } } } while (0)
; __device__ __forceinline__ void xcd_barrier(const XcdBarrier& b) {
;     asm volatile("s_waitcnt vmcnt(0)" ::: "memory");
;     __syncthreads();
;     if (threadIdx.x == 0) {
;         unsigned* bar = b.bar;
;         __builtin_amdgcn_s_waitcnt(0);
;         unsigned nloc = b.st[0], nx = b.st[1];
;         if (nloc == 0u) { xcd_barrier_complete(bar, b.x, nloc, nx); b.st[0] = nloc; b.st[1] = nx; }
;         const unsigned old = xb_add(&bar[XB_XSUB(b.x)], 1u);
;         const unsigned gen = old / nloc;
;         if (old + 1u == (gen + 1u) * nloc) {
;             __builtin_amdgcn_fence(__ATOMIC_RELEASE, "agent");
;             asm volatile("s_waitcnt vmcnt(0)" ::: "memory");
;             const unsigned og = xb_add(&bar[XB_TOP], 1u);
;             const unsigned tg = og / nx;
;             if (og + 1u == (tg + 1u) * nx) xb_add(&bar[XB_TOPGEN], 1u);
;             else XB_SPIN(xb_ld(&bar[XB_TOPGEN]) == tg, bar);
;             __builtin_amdgcn_fence(__ATOMIC_ACQUIRE, "agent");
;             xb_add(&bar[XB_XGEN(b.x)], 1u);
;             asm volatile("s_waitcnt vmcnt(0)" ::: "memory");
;         } else {
;             XB_SPIN(xb_ld(&bar[XB_XGEN(b.x)]) == gen, bar);
;             __builtin_amdgcn_fence(__ATOMIC_ACQUIRE, "agent");
;             asm volatile("s_waitcnt vmcnt(0)" ::: "memory");
;         }
;     }
;     __syncthreads();
; }
.LBB0_466:
	s_or_b32 s10, s58, 2
	s_cmp_ge_i32 s10, s19
	s_cbranch_scc1 .LBB0_520
	v_mov_b32_e32 v0, s42
	ds_read_b64 v[2:3], v0
	s_getreg_b32 s6, hwreg(HW_REG_XCC_ID, 0, 4)
	s_waitcnt vmcnt(0)
	s_waitcnt vmcnt(0) lgkmcnt(0)
	s_barrier
	v_readfirstlane_b32 s5, v3
	v_readfirstlane_b32 s4, v2
	s_and_saveexec_b64 s[0:1], s[78:79]
	s_cbranch_execz .LBB0_519
	v_mov_b32_e32 v0, 0x250d0
	ds_read_b64 v[6:7], v0
	v_mov_b32_e32 v0, 0x25100
	ds_read2_b32 v[8:9], v0 offset1:2
	s_getreg_b32 s12, hwreg(HW_REG_XCC_ID, 0, 4)
	s_waitcnt vmcnt(0) lgkmcnt(0)
	v_readfirstlane_b32 s40, v6
	v_readfirstlane_b32 s41, v7
	v_readfirstlane_b32 s14, v8
	v_readfirstlane_b32 s17, v9
	s_add_u32 s40, s40, 0x1e600000
	s_addc_u32 s41, s41, 0
	s_and_b32 s12, s12, 15
	s_add_i32 s17, s17, 1
	v_mov_b32_e32 v8, s17
	ds_write_b32 v0, v8 offset:8
	s_mul_i32 s28, s17, s14
	s_mul_i32 s30, s17, s34
	s_lshl_b32 s31, s12, 8
	s_add_i32 s31, s31, 0x8000
	v_mov_b32_e32 v0, s31
	v_mov_b32_e32 v6, 1
	global_atomic_add v6, v0, v6, s[40:41] sc0
	s_waitcnt vmcnt(0)
	v_readfirstlane_b32 s31, v6
	s_add_i32 s31, s31, 1
	s_cmp_lg_u32 s31, s28
	s_cbranch_scc1 .Lsb0_wait
	buffer_wbl2 sc1
	s_waitcnt vmcnt(0)
	v_mov_b32_e32 v0, 0x9000
	v_mov_b32_e32 v6, s14
	global_atomic_add v0, v6, s[40:41]
.Lsb0_wait:
	v_mov_b32_e32 v0, 0x9000
	s_mov_b32 s31, 0
.Lsb0_spin:
	global_load_dword v6, v0, s[40:41] sc1
	s_waitcnt vmcnt(0)
	v_readfirstlane_b32 s44, v6
	s_cmp_ge_u32 s44, s30
	s_cbranch_scc1 .Lsb0_acq
	s_sleep 1
	s_add_i32 s31, s31, 1
	s_cmp_lt_u32 s31, 0x8000
	s_cbranch_scc1 .Lsb0_spin
.Lsb0_acq:
	buffer_inv sc1
	s_waitcnt vmcnt(0) lgkmcnt(0)

; __device__ __forceinline__ unsigned xb_ld(unsigned* p)              { return __hip_atomic_load(p, __ATOMIC_RELAXED, __HIP_MEMORY_SCOPE_AGENT); }
; __device__ __forceinline__ unsigned xb_add(unsigned* p, unsigned v) { return __hip_atomic_fetch_add(p, v, __ATOMIC_RELAXED, __HIP_MEMORY_SCOPE_AGENT); }
; #define XB_SPIN(cond, bar) do { unsigned _sp = 0; while (cond) { __builtin_amdgcn_s_sleep(1); \
;     if ((++_sp & 255u) == 0u) { if (xb_ld(&(bar)[XB_TMO])) break; if (_sp > XB_SPIN_CAP) { atomicAdd(&(bar)[XB_TMO], 1u); break; } } } } while (0)
; __device__ __forceinline__ void xcd_barrier(const XcdBarrier& b) {
;     asm volatile("s_waitcnt vmcnt(0)" ::: "memory");
;     __syncthreads();
;     if (threadIdx.x == 0) {
;         unsigned* bar = b.bar;
;         __builtin_amdgcn_s_waitcnt(0);
;         unsigned nloc = b.st[0], nx = b.st[1];
;         if (nloc == 0u) { xcd_barrier_complete(bar, b.x, nloc, nx); b.st[0] = nloc; b.st[1] = nx; }
;         const unsigned old = xb_add(&bar[XB_XSUB(b.x)], 1u);
;         const unsigned gen = old / nloc;
;         if (old + 1u == (gen + 1u) * nloc) {
;             __builtin_amdgcn_fence(__ATOMIC_RELEASE, "agent");
;             asm volatile("s_waitcnt vmcnt(0)" ::: "memory");
;             const unsigned og = xb_add(&bar[XB_TOP], 1u);
;             const unsigned tg = og / nx;
;             if (og + 1u == (tg + 1u) * nx) xb_add(&bar[XB_TOPGEN], 1u);
;             else XB_SPIN(xb_ld(&bar[XB_TOPGEN]) == tg, bar);
;             __builtin_amdgcn_fence(__ATOMIC_ACQUIRE, "agent");
;             xb_add(&bar[XB_XGEN(b.x)], 1u);
;             asm volatile("s_waitcnt vmcnt(0)" ::: "memory");
;         } else {
;             XB_SPIN(xb_ld(&bar[XB_XGEN(b.x)]) == gen, bar);
;             __builtin_amdgcn_fence(__ATOMIC_ACQUIRE, "agent");
;             asm volatile("s_waitcnt vmcnt(0)" ::: "memory");
;         }
;     }
;     __syncthreads();
; }
.LBB0_793:
	s_or_b32 s4, s58, 4
	s_cmp_ge_i32 s4, s19
	s_cbranch_scc1 .LBB0_847
	v_mov_b32_e32 v0, s42
	ds_read_b64 v[2:3], v0
	s_getreg_b32 s5, hwreg(HW_REG_XCC_ID, 0, 4)
	s_waitcnt vmcnt(0)
	s_waitcnt vmcnt(0) lgkmcnt(0)
	s_barrier
	v_readfirstlane_b32 s7, v3
	v_readfirstlane_b32 s6, v2
	s_and_saveexec_b64 s[0:1], s[78:79]
	s_cbranch_execz .LBB0_846
	v_mov_b32_e32 v0, 0x250d0
	ds_read_b64 v[6:7], v0
	v_mov_b32_e32 v0, 0x25100
	ds_read2_b32 v[8:9], v0 offset1:2
	s_getreg_b32 s12, hwreg(HW_REG_XCC_ID, 0, 4)
	s_waitcnt vmcnt(0) lgkmcnt(0)
	v_readfirstlane_b32 s40, v6
	v_readfirstlane_b32 s41, v7
	v_readfirstlane_b32 s14, v8
	v_readfirstlane_b32 s17, v9
	s_add_u32 s40, s40, 0x1e600000
	s_addc_u32 s41, s41, 0
	s_and_b32 s12, s12, 15
	s_add_i32 s17, s17, 1
	v_mov_b32_e32 v8, s17
	ds_write_b32 v0, v8 offset:8
	s_mul_i32 s28, s17, s14
	s_mul_i32 s30, s17, s34
	s_lshl_b32 s31, s12, 8
	s_add_i32 s31, s31, 0x8000
	v_mov_b32_e32 v0, s31
	v_mov_b32_e32 v6, 1
	global_atomic_add v6, v0, v6, s[40:41] sc0
	s_waitcnt vmcnt(0)
	v_readfirstlane_b32 s31, v6
	s_add_i32 s31, s31, 1
	s_cmp_lg_u32 s31, s28
	s_cbranch_scc1 .Lsb2_wait
	buffer_wbl2 sc1
	s_waitcnt vmcnt(0)
	v_mov_b32_e32 v0, 0x9000
	v_mov_b32_e32 v6, s14
	global_atomic_add v0, v6, s[40:41]

; __device__ __forceinline__ unsigned xb_ld(unsigned* p)              { return __hip_atomic_load(p, __ATOMIC_RELAXED, __HIP_MEMORY_SCOPE_AGENT); }
; __device__ __forceinline__ unsigned xb_add(unsigned* p, unsigned v) { return __hip_atomic_fetch_add(p, v, __ATOMIC_RELAXED, __HIP_MEMORY_SCOPE_AGENT); }
; #define XB_SPIN(cond, bar) do { unsigned _sp = 0; while (cond) { __builtin_amdgcn_s_sleep(1); \
;     if ((++_sp & 255u) == 0u) { if (xb_ld(&(bar)[XB_TMO])) break; if (_sp > XB_SPIN_CAP) { atomicAdd(&(bar)[XB_TMO], 1u); break; } } } } while (0)
; __device__ __forceinline__ void xcd_barrier(const XcdBarrier& b) {
;     asm volatile("s_waitcnt vmcnt(0)" ::: "memory");
;     __syncthreads();
;     if (threadIdx.x == 0) {
;         unsigned* bar = b.bar;
;         __builtin_amdgcn_s_waitcnt(0);
;         unsigned nloc = b.st[0], nx = b.st[1];
;         if (nloc == 0u) { xcd_barrier_complete(bar, b.x, nloc, nx); b.st[0] = nloc; b.st[1] = nx; }
;         const unsigned old = xb_add(&bar[XB_XSUB(b.x)], 1u);
;         const unsigned gen = old / nloc;
;         if (old + 1u == (gen + 1u) * nloc) {
;             __builtin_amdgcn_fence(__ATOMIC_RELEASE, "agent");
;             asm volatile("s_waitcnt vmcnt(0)" ::: "memory");
;             const unsigned og = xb_add(&bar[XB_TOP], 1u);
;             const unsigned tg = og / nx;
;             if (og + 1u == (tg + 1u) * nx) xb_add(&bar[XB_TOPGEN], 1u);
;             else XB_SPIN(xb_ld(&bar[XB_TOPGEN]) == tg, bar);
;             __builtin_amdgcn_fence(__ATOMIC_ACQUIRE, "agent");
;             xb_add(&bar[XB_XGEN(b.x)], 1u);
;             asm volatile("s_waitcnt vmcnt(0)" ::: "memory");
;         } else {
;             XB_SPIN(xb_ld(&bar[XB_XGEN(b.x)]) == gen, bar);
;             __builtin_amdgcn_fence(__ATOMIC_ACQUIRE, "agent");
;             asm volatile("s_waitcnt vmcnt(0)" ::: "memory");
;         }
;     }
;     __syncthreads();
; }
.LBB0_909:
	s_or_b32 s4, s58, 5
	s_cmp_ge_i32 s4, s19
	s_cbranch_scc1 .LBB0_963
	v_mov_b32_e32 v0, s42
	ds_read_b64 v[2:3], v0
	s_getreg_b32 s5, hwreg(HW_REG_XCC_ID, 0, 4)
	s_waitcnt vmcnt(0)
	s_waitcnt vmcnt(0) lgkmcnt(0)
	s_barrier
	v_readfirstlane_b32 s7, v3
	v_readfirstlane_b32 s6, v2
	s_and_saveexec_b64 s[0:1], s[78:79]
	s_cbranch_execz .LBB0_962
	v_mov_b32_e32 v0, 0x250d0
	ds_read_b64 v[6:7], v0
	v_mov_b32_e32 v0, 0x25100
	ds_read2_b32 v[8:9], v0 offset1:2
	s_getreg_b32 s12, hwreg(HW_REG_XCC_ID, 0, 4)
	s_waitcnt vmcnt(0) lgkmcnt(0)
	v_readfirstlane_b32 s40, v6
	v_readfirstlane_b32 s41, v7
	v_readfirstlane_b32 s14, v8
	v_readfirstlane_b32 s17, v9
	s_add_u32 s40, s40, 0x1e600000
	s_addc_u32 s41, s41, 0
	s_and_b32 s12, s12, 15
	s_add_i32 s17, s17, 1
	v_mov_b32_e32 v8, s17
	ds_write_b32 v0, v8 offset:8
	s_mul_i32 s28, s17, s14
	s_mul_i32 s30, s17, s34
	s_lshl_b32 s31, s12, 8
	s_add_i32 s31, s31, 0x8000
	v_mov_b32_e32 v0, s31
	v_mov_b32_e32 v6, 1
	global_atomic_add v6, v0, v6, s[40:41] sc0
	s_waitcnt vmcnt(0)
	v_readfirstlane_b32 s31, v6
	s_add_i32 s31, s31, 1
	s_cmp_lg_u32 s31, s28
	s_cbranch_scc1 .Lsb3_wait
	buffer_wbl2 sc1
	s_waitcnt vmcnt(0)
	v_mov_b32_e32 v0, 0x9000
	v_mov_b32_e32 v6, s14
	global_atomic_add v0, v6, s[40:41]

; __device__ __forceinline__ unsigned xb_ld(unsigned* p)              { return __hip_atomic_load(p, __ATOMIC_RELAXED, __HIP_MEMORY_SCOPE_AGENT); }
; __device__ __forceinline__ unsigned xb_add(unsigned* p, unsigned v) { return __hip_atomic_fetch_add(p, v, __ATOMIC_RELAXED, __HIP_MEMORY_SCOPE_AGENT); }
; #define XB_SPIN(cond, bar) do { unsigned _sp = 0; while (cond) { __builtin_amdgcn_s_sleep(1); \
;     if ((++_sp & 255u) == 0u) { if (xb_ld(&(bar)[XB_TMO])) break; if (_sp > XB_SPIN_CAP) { atomicAdd(&(bar)[XB_TMO], 1u); break; } } } } while (0)
; __device__ __forceinline__ void xcd_barrier(const XcdBarrier& b) {
;     asm volatile("s_waitcnt vmcnt(0)" ::: "memory");
;     __syncthreads();
;     if (threadIdx.x == 0) {
;         unsigned* bar = b.bar;
;         __builtin_amdgcn_s_waitcnt(0);
;         unsigned nloc = b.st[0], nx = b.st[1];
;         if (nloc == 0u) { xcd_barrier_complete(bar, b.x, nloc, nx); b.st[0] = nloc; b.st[1] = nx; }
;         const unsigned old = xb_add(&bar[XB_XSUB(b.x)], 1u);
;         const unsigned gen = old / nloc;
;         if (old + 1u == (gen + 1u) * nloc) {
;             __builtin_amdgcn_fence(__ATOMIC_RELEASE, "agent");
;             asm volatile("s_waitcnt vmcnt(0)" ::: "memory");
;             const unsigned og = xb_add(&bar[XB_TOP], 1u);
;             const unsigned tg = og / nx;
;             if (og + 1u == (tg + 1u) * nx) xb_add(&bar[XB_TOPGEN], 1u);
;             else XB_SPIN(xb_ld(&bar[XB_TOPGEN]) == tg, bar);
;             __builtin_amdgcn_fence(__ATOMIC_ACQUIRE, "agent");
;             xb_add(&bar[XB_XGEN(b.x)], 1u);
;             asm volatile("s_waitcnt vmcnt(0)" ::: "memory");
;         } else {
;             XB_SPIN(xb_ld(&bar[XB_XGEN(b.x)]) == gen, bar);
;             __builtin_amdgcn_fence(__ATOMIC_ACQUIRE, "agent");
;             asm volatile("s_waitcnt vmcnt(0)" ::: "memory");
;         }
;     }
;     __syncthreads();
; }
.LBB0_994:
	v_mov_b32_e32 v0, s42
	ds_read_b64 v[2:3], v0
	s_getreg_b32 s5, hwreg(HW_REG_XCC_ID, 0, 4)
	s_waitcnt vmcnt(0)
	s_waitcnt vmcnt(0) lgkmcnt(0)
	s_barrier
	v_readfirstlane_b32 s7, v3
	v_readfirstlane_b32 s6, v2
	s_and_saveexec_b64 s[0:1], s[78:79]
	s_cbranch_execz .LBB0_1046
	v_mov_b32_e32 v0, 0x250d0
	ds_read_b64 v[6:7], v0
	v_mov_b32_e32 v0, 0x25100
	ds_read2_b32 v[8:9], v0 offset1:2
	s_getreg_b32 s12, hwreg(HW_REG_XCC_ID, 0, 4)
	s_waitcnt vmcnt(0) lgkmcnt(0)
	v_readfirstlane_b32 s40, v6
	v_readfirstlane_b32 s41, v7
	v_readfirstlane_b32 s14, v8
	v_readfirstlane_b32 s17, v9
	s_add_u32 s40, s40, 0x1e600000
	s_addc_u32 s41, s41, 0
	s_and_b32 s12, s12, 15
	s_add_i32 s17, s17, 1
	v_mov_b32_e32 v8, s17
	ds_write_b32 v0, v8 offset:8
	s_mul_i32 s28, s17, s14
	s_mul_i32 s30, s17, s34
	s_lshl_b32 s31, s12, 8
	s_add_i32 s31, s31, 0x8000
	v_mov_b32_e32 v0, s31
	v_mov_b32_e32 v6, 1
	global_atomic_add v6, v0, v6, s[40:41] sc0
	s_waitcnt vmcnt(0)
	v_readfirstlane_b32 s31, v6
	s_add_i32 s31, s31, 1
	s_cmp_lg_u32 s31, s28
	s_cbranch_scc1 .Lsb4_wait
	buffer_wbl2 sc1
	s_waitcnt vmcnt(0)
	v_mov_b32_e32 v0, 0x9000
	v_mov_b32_e32 v6, s14
	global_atomic_add v0, v6, s[40:41]

; __device__ __forceinline__ unsigned xb_ld(unsigned* p)              { return __hip_atomic_load(p, __ATOMIC_RELAXED, __HIP_MEMORY_SCOPE_AGENT); }
; __device__ __forceinline__ unsigned xb_add(unsigned* p, unsigned v) { return __hip_atomic_fetch_add(p, v, __ATOMIC_RELAXED, __HIP_MEMORY_SCOPE_AGENT); }
; #define XB_SPIN(cond, bar) do { unsigned _sp = 0; while (cond) { __builtin_amdgcn_s_sleep(1); \
;     if ((++_sp & 255u) == 0u) { if (xb_ld(&(bar)[XB_TMO])) break; if (_sp > XB_SPIN_CAP) { atomicAdd(&(bar)[XB_TMO], 1u); break; } } } } while (0)
; __device__ __forceinline__ void xcd_barrier(const XcdBarrier& b) {
;     asm volatile("s_waitcnt vmcnt(0)" ::: "memory");
;     __syncthreads();
;     if (threadIdx.x == 0) {
;         unsigned* bar = b.bar;
;         __builtin_amdgcn_s_waitcnt(0);
;         unsigned nloc = b.st[0], nx = b.st[1];
;         if (nloc == 0u) { xcd_barrier_complete(bar, b.x, nloc, nx); b.st[0] = nloc; b.st[1] = nx; }
;         const unsigned old = xb_add(&bar[XB_XSUB(b.x)], 1u);
;         const unsigned gen = old / nloc;
;         if (old + 1u == (gen + 1u) * nloc) {
;             __builtin_amdgcn_fence(__ATOMIC_RELEASE, "agent");
;             asm volatile("s_waitcnt vmcnt(0)" ::: "memory");
;             const unsigned og = xb_add(&bar[XB_TOP], 1u);
;             const unsigned tg = og / nx;
;             if (og + 1u == (tg + 1u) * nx) xb_add(&bar[XB_TOPGEN], 1u);
;             else XB_SPIN(xb_ld(&bar[XB_TOPGEN]) == tg, bar);
;             __builtin_amdgcn_fence(__ATOMIC_ACQUIRE, "agent");
;             xb_add(&bar[XB_XGEN(b.x)], 1u);
;             asm volatile("s_waitcnt vmcnt(0)" ::: "memory");
;         } else {
;             XB_SPIN(xb_ld(&bar[XB_XGEN(b.x)]) == gen, bar);
;             __builtin_amdgcn_fence(__ATOMIC_ACQUIRE, "agent");
;             asm volatile("s_waitcnt vmcnt(0)" ::: "memory");
;         }
;     }
;     __syncthreads();
; }
.LBB0_1086:
	s_or_b32 s4, s58, 7
	s_cmp_ge_i32 s4, s19
	s_cbranch_scc1 .LBB0_1140
	v_mov_b32_e32 v0, s42
	ds_read_b64 v[2:3], v0
	s_getreg_b32 s5, hwreg(HW_REG_XCC_ID, 0, 4)
	s_waitcnt vmcnt(0)
	s_waitcnt vmcnt(0) lgkmcnt(0)
	s_barrier
	v_readfirstlane_b32 s7, v3
	v_readfirstlane_b32 s6, v2
	s_and_saveexec_b64 s[0:1], s[78:79]
	s_cbranch_execz .LBB0_1139
	v_mov_b32_e32 v0, 0x250d0
	ds_read_b64 v[6:7], v0
	v_mov_b32_e32 v0, 0x25100
	ds_read2_b32 v[8:9], v0 offset1:2
	s_getreg_b32 s12, hwreg(HW_REG_XCC_ID, 0, 4)
	s_waitcnt vmcnt(0) lgkmcnt(0)
	v_readfirstlane_b32 s40, v6
	v_readfirstlane_b32 s41, v7
	v_readfirstlane_b32 s14, v8
	v_readfirstlane_b32 s17, v9
	s_add_u32 s40, s40, 0x1e600000
	s_addc_u32 s41, s41, 0
	s_and_b32 s12, s12, 15
	s_add_i32 s17, s17, 1
	v_mov_b32_e32 v8, s17
	ds_write_b32 v0, v8 offset:8
	s_mul_i32 s28, s17, s14
	s_mul_i32 s30, s17, s34
	s_lshl_b32 s31, s12, 8
	s_add_i32 s31, s31, 0x8000
	v_mov_b32_e32 v0, s31
	v_mov_b32_e32 v6, 1
	global_atomic_add v6, v0, v6, s[40:41] sc0
	s_waitcnt vmcnt(0)
	v_readfirstlane_b32 s31, v6
	s_add_i32 s31, s31, 1
	s_cmp_lg_u32 s31, s28
	s_cbranch_scc1 .Lsb5_wait
	buffer_wbl2 sc1
	s_waitcnt vmcnt(0)
	v_mov_b32_e32 v0, 0x9000
	v_mov_b32_e32 v6, s14
	global_atomic_add v0, v6, s[40:41]

; __device__ __forceinline__ unsigned xb_ld(unsigned* p)              { return __hip_atomic_load(p, __ATOMIC_RELAXED, __HIP_MEMORY_SCOPE_AGENT); }
; __device__ __forceinline__ unsigned xb_add(unsigned* p, unsigned v) { return __hip_atomic_fetch_add(p, v, __ATOMIC_RELAXED, __HIP_MEMORY_SCOPE_AGENT); }
; #define XB_SPIN(cond, bar) do { unsigned _sp = 0; while (cond) { __builtin_amdgcn_s_sleep(1); \
;     if ((++_sp & 255u) == 0u) { if (xb_ld(&(bar)[XB_TMO])) break; if (_sp > XB_SPIN_CAP) { atomicAdd(&(bar)[XB_TMO], 1u); break; } } } } while (0)
; __device__ __forceinline__ void xcd_barrier(const XcdBarrier& b) {
;     asm volatile("s_waitcnt vmcnt(0)" ::: "memory");
;     __syncthreads();
;     if (threadIdx.x == 0) {
;         unsigned* bar = b.bar;
;         __builtin_amdgcn_s_waitcnt(0);
;         unsigned nloc = b.st[0], nx = b.st[1];
;         if (nloc == 0u) { xcd_barrier_complete(bar, b.x, nloc, nx); b.st[0] = nloc; b.st[1] = nx; }
;         const unsigned old = xb_add(&bar[XB_XSUB(b.x)], 1u);
;         const unsigned gen = old / nloc;
;         if (old + 1u == (gen + 1u) * nloc) {
;             __builtin_amdgcn_fence(__ATOMIC_RELEASE, "agent");
;             asm volatile("s_waitcnt vmcnt(0)" ::: "memory");
;             const unsigned og = xb_add(&bar[XB_TOP], 1u);
;             const unsigned tg = og / nx;
;             if (og + 1u == (tg + 1u) * nx) xb_add(&bar[XB_TOPGEN], 1u);
;             else XB_SPIN(xb_ld(&bar[XB_TOPGEN]) == tg, bar);
;             __builtin_amdgcn_fence(__ATOMIC_ACQUIRE, "agent");
;             xb_add(&bar[XB_XGEN(b.x)], 1u);
;             asm volatile("s_waitcnt vmcnt(0)" ::: "memory");
;         } else {
;             XB_SPIN(xb_ld(&bar[XB_XGEN(b.x)]) == gen, bar);
;             __builtin_amdgcn_fence(__ATOMIC_ACQUIRE, "agent");
;             asm volatile("s_waitcnt vmcnt(0)" ::: "memory");
;         }
;     }
;     __syncthreads();
; }
.LBB0_1204:
	s_add_i32 s4, s58, 8
	s_cmp_ge_i32 s4, s19
	s_cbranch_scc1 .LBB0_1258
	v_mov_b32_e32 v0, s42
	ds_read_b64 v[2:3], v0
	s_getreg_b32 s5, hwreg(HW_REG_XCC_ID, 0, 4)
	s_waitcnt vmcnt(0)
	s_waitcnt lgkmcnt(0)
	s_barrier
	v_readfirstlane_b32 s7, v3
	v_readfirstlane_b32 s6, v2
	s_and_saveexec_b64 s[0:1], s[78:79]
	s_cbranch_execz .LBB0_1257
	v_mov_b32_e32 v0, 0x250d0
	ds_read_b64 v[6:7], v0
	v_mov_b32_e32 v0, 0x25100
	ds_read2_b32 v[8:9], v0 offset1:2
	s_getreg_b32 s12, hwreg(HW_REG_XCC_ID, 0, 4)
	s_waitcnt vmcnt(0) lgkmcnt(0)
	v_readfirstlane_b32 s40, v6
	v_readfirstlane_b32 s41, v7
	v_readfirstlane_b32 s14, v8
	v_readfirstlane_b32 s17, v9
	s_add_u32 s40, s40, 0x1e600000
	s_addc_u32 s41, s41, 0
	s_and_b32 s12, s12, 15
	s_add_i32 s17, s17, 1
	v_mov_b32_e32 v8, s17
	ds_write_b32 v0, v8 offset:8
	s_mul_i32 s28, s17, s14
	s_mul_i32 s30, s17, s34
	s_lshl_b32 s31, s12, 8
	s_add_i32 s31, s31, 0x8000
	v_mov_b32_e32 v0, s31
	v_mov_b32_e32 v6, 1
	global_atomic_add v6, v0, v6, s[40:41] sc0
	s_waitcnt vmcnt(0)
	v_readfirstlane_b32 s31, v6
	s_add_i32 s31, s31, 1
	s_cmp_lg_u32 s31, s28
	s_cbranch_scc1 .Lsb6_wait
	buffer_wbl2 sc1
	s_waitcnt vmcnt(0)
	v_mov_b32_e32 v0, 0x9000
	v_mov_b32_e32 v6, s14
	global_atomic_add v0, v6, s[40:41]
